# phase 2 scoring loop: one static s_setprio 1 for waves 4-7 (younger half), reset after the loop
# baseline (speedup 1.0000x reference)
; __device__ void phase2(const Params& p, unsigned char* smem) {
;     ...
;       const int nchunk = nvis >> 6;
;       const u16* kbase = KI + (size_t)n16 * 64 + 8 * g4;
;       bf16x8 nA0, nB0, nA1, nB1, nA2, nB2, nA3, nB3;
;       int c = wave;
;       if (c < nchunk) P2_LOADCHUNK(c, nA0, nB0, nA1, nB1, nA2, nB2, nA3, nB3)
;       for (; c < nchunk; c += 8) {
;         bf16x8 cA0 = nA0, cB0 = nB0, cA1 = nA1, cB1 = nB1, cA2 = nA2, cB2 = nB2, cA3 = nA3, cB3 = nB3;
;         if (c + 8 < nchunk) P2_LOADCHUNK(c + 8, nA0, nB0, nA1, nB1, nA2, nB2, nA3, nB3)
;         __builtin_amdgcn_sched_barrier(0);
;         P2_SCORE(cA0, cB0, c * 4 + 0)
;         P2_SCORE(cA1, cB1, c * 4 + 1)
;         P2_SCORE(cA2, cB2, c * 4 + 2)
;         P2_SCORE(cA3, cB3, c * 4 + 3)
;       }
.LBB0_548:
	s_or_b64 exec, exec, s[38:39]
	s_and_saveexec_b64 s[38:39], s[36:37]
	s_cbranch_execz .LBB0_554
	s_waitcnt vmcnt(0)
	v_readfirstlane_b32 s40, v133
	v_lshl_add_u64 v[142:143], s[48:49], 0, v[134:135]
	v_lshrrev_b32_e32 v202, 4, v154
	v_and_b32_e32 v203, 1, v202
	v_lshrrev_b32_e32 v204, 1, v202
	v_lshl_or_b32 v203, v203, 1, v204
	v_lshlrev_b32_e32 v203, 14, v203
	v_and_b32_e32 v204, 15, v154
	v_lshl_or_b32 v210, v204, 1, v203
	v_lshl_add_u32 v210, v133, 7, v210
	v_add_co_u32_e32 v208, vcc, 0x1000, v142
	v_add_u32_e32 v211, 0x10000, v210
	v_addc_co_u32_e32 v209, vcc, 0, v143, vcc
	s_add_i32 s41, s40, 8
	s_cmp_lt_u32 s40, 4
	s_cbranch_scc1 .Lsc_noprio
	s_setprio 1
.Lsc_noprio:
.Lsc_loop:
	s_cmp_lt_u32 s41, s47
	s_cselect_b64 vcc, 0, -1
	s_waitcnt vmcnt(6)
	v_mfma_f32_16x16x32_bf16 v[168:171], v[38:41], v[34:37], 0
	v_mfma_f32_16x16x32_bf16 v[172:175], v[50:53], v[34:37], 0
	v_mfma_f32_16x16x32_bf16 v[176:179], v[62:65], v[34:37], 0
	v_mfma_f32_16x16x32_bf16 v[180:183], v[74:77], v[34:37], 0
	v_mfma_f32_16x16x32_bf16 v[168:171], v[42:45], v[30:33], v[168:171]
	v_mfma_f32_16x16x32_bf16 v[172:175], v[54:57], v[30:33], v[172:175]
	v_mfma_f32_16x16x32_bf16 v[176:179], v[66:69], v[30:33], v[176:179]
	v_mfma_f32_16x16x32_bf16 v[180:183], v[78:81], v[30:33], v[180:183]
	s_cbranch_vccnz .Lsc_np0
	global_load_dwordx4 v[34:37], v[142:143], off
	global_load_dwordx4 v[30:33], v[142:143], off offset:64
	s_branch .Lsc_c0

; __device__ void phase2(const Params& p, unsigned char* smem) {
;     ...
;       for (; c < nchunk; c += 8) {
;         bf16x8 cA0 = nA0, cB0 = nB0, cA1 = nA1, cB1 = nB1, cA2 = nA2, cB2 = nB2, cA3 = nA3, cB3 = nB3;
;         if (c + 8 < nchunk) P2_LOADCHUNK(c + 8, nA0, nB0, nA1, nB1, nA2, nB2, nA3, nB3)
;         __builtin_amdgcn_sched_barrier(0);
;         P2_SCORE(cA0, cB0, c * 4 + 0)
;         P2_SCORE(cA1, cB1, c * 4 + 1)
;         P2_SCORE(cA2, cB2, c * 4 + 2)
;         P2_SCORE(cA3, cB3, c * 4 + 3)
;       }
.Lsc_c3:
	v_max_f32_e32 v169, 0, v169
	v_max_f32_e32 v168, 0, v168
	v_mul_f32_e32 v169, v47, v169
	v_max_f32_e32 v170, 0, v170
	v_fmac_f32_e32 v169, v46, v168
	v_max_f32_e32 v171, 0, v171
	v_fmac_f32_e32 v169, v48, v170
	v_fmac_f32_e32 v169, v49, v171
	v_max_f32_e32 v173, 0, v173
	v_max_f32_e32 v172, 0, v172
	v_mul_f32_e32 v173, v59, v173
	v_max_f32_e32 v174, 0, v174
	v_fmac_f32_e32 v173, v58, v172
	v_max_f32_e32 v175, 0, v175
	v_fmac_f32_e32 v173, v60, v174
	v_fmac_f32_e32 v173, v61, v175
	v_max_f32_e32 v177, 0, v177
	v_max_f32_e32 v176, 0, v176
	v_permlane16_swap_b32_e32 v169, v173
	v_add_f32_e32 v200, v169, v173
	v_cvt_f16_f32_e32 v200, v200
	v_bfe_i32 v202, v200, 15, 1
	v_bitop3_b16 v200, v202, v200, s71 bitop3:0x36
	ds_write_b16 v210, v200 offset:64
	v_mul_f32_e32 v177, v71, v177
	v_max_f32_e32 v178, 0, v178
	v_fmac_f32_e32 v177, v70, v176
	v_max_f32_e32 v179, 0, v179
	v_fmac_f32_e32 v177, v72, v178
	v_fmac_f32_e32 v177, v73, v179
	v_max_f32_e32 v181, 0, v181
	v_max_f32_e32 v180, 0, v180
	v_mul_f32_e32 v181, v83, v181
	v_max_f32_e32 v182, 0, v182
	v_fmac_f32_e32 v181, v82, v180
	v_max_f32_e32 v183, 0, v183
	v_fmac_f32_e32 v181, v84, v182
	v_fmac_f32_e32 v181, v85, v183
	s_nop 1
	v_permlane16_swap_b32_e32 v177, v181
	v_add_f32_e32 v201, v177, v181
	v_cvt_f16_f32_e32 v201, v201
	v_bfe_i32 v202, v201, 15, 1
	v_bitop3_b16 v201, v202, v201, s71 bitop3:0x36
	ds_write_b16 v211, v201 offset:64
	v_max_f32_e32 v185, 0, v185
	v_max_f32_e32 v184, 0, v184
	v_mul_f32_e32 v185, v47, v185
	v_max_f32_e32 v186, 0, v186
	v_fmac_f32_e32 v185, v46, v184
	v_max_f32_e32 v187, 0, v187
	v_fmac_f32_e32 v185, v48, v186
	v_fmac_f32_e32 v185, v49, v187
	v_max_f32_e32 v189, 0, v189
	v_max_f32_e32 v188, 0, v188
	v_mul_f32_e32 v189, v59, v189
	v_max_f32_e32 v190, 0, v190
	v_fmac_f32_e32 v189, v58, v188
	v_max_f32_e32 v191, 0, v191
	v_fmac_f32_e32 v189, v60, v190
	v_fmac_f32_e32 v189, v61, v191
	v_max_f32_e32 v193, 0, v193
	v_max_f32_e32 v192, 0, v192
	v_permlane16_swap_b32_e32 v185, v189
	v_add_f32_e32 v200, v185, v189
	v_cvt_f16_f32_e32 v200, v200
	v_bfe_i32 v202, v200, 15, 1
	v_bitop3_b16 v200, v202, v200, s71 bitop3:0x36
	ds_write_b16 v210, v200 offset:96
	v_mul_f32_e32 v193, v71, v193
	v_max_f32_e32 v194, 0, v194
	v_fmac_f32_e32 v193, v70, v192
	v_max_f32_e32 v195, 0, v195
	v_fmac_f32_e32 v193, v72, v194
	v_fmac_f32_e32 v193, v73, v195
	v_max_f32_e32 v197, 0, v197
	v_max_f32_e32 v196, 0, v196
	v_mul_f32_e32 v197, v83, v197
	v_max_f32_e32 v198, 0, v198
	v_fmac_f32_e32 v197, v82, v196
	v_max_f32_e32 v199, 0, v199
	v_fmac_f32_e32 v197, v84, v198
	v_fmac_f32_e32 v197, v85, v199
	s_nop 1
	v_permlane16_swap_b32_e32 v193, v197
	v_add_f32_e32 v201, v193, v197
	v_cvt_f16_f32_e32 v201, v201
	v_bfe_i32 v202, v201, 15, 1
	v_bitop3_b16 v201, v202, v201, s71 bitop3:0x36
	ds_write_b16 v211, v201 offset:96
	v_lshl_add_u64 v[142:143], v[142:143], 0, s[60:61]
	v_lshl_add_u64 v[208:209], v[208:209], 0, s[60:61]
	v_add_u32_e32 v210, 0x400, v210
	v_add_u32_e32 v211, 0x400, v211
	s_add_i32 s40, s40, 8
	s_add_i32 s41, s41, 8
	s_cmp_lt_u32 s40, s47
	s_cbranch_scc1 .Lsc_loop
	s_setprio 0
